# P4 epilogue touch-prefetch with default-policy touches
# speedup vs baseline: 1.0008x; 1.0008x over previous
.LBB0_666:
	s_lshl_b32 s10, s6, 8
	s_add_i32 s1, s10, s38
	s_lshl_b32 s0, s7, 5
	v_or_b32_e32 v130, s1, v145
	s_lshl_b32 s1, s8, 8
	s_or_b32 s0, s1, s0
	v_lshrrev_b32_e32 v128, 2, v144
	v_ashrrev_i32_e32 v131, 31, v130
	v_and_or_b32 v128, v128, 12, s0
	v_lshlrev_b64 v[132:133], 13, v[130:131]
	v_ashrrev_i32_e32 v129, 31, v128
	v_lshl_add_u64 v[132:133], s[44:45], 0, v[132:133]
	v_lshl_add_u64 v[148:149], v[128:129], 2, v[132:133]
	s_barrier
	global_load_dwordx4 v[132:135], v[148:149], off nt
	global_load_dwordx4 v[136:139], v[148:149], off offset:64 nt
	global_load_dwordx4 v[140:143], v[148:149], off offset:512 nt
	global_load_dwordx4 v[150:153], v[148:149], off offset:576 nt
	v_mov_b32_e32 v178, v148
	v_mov_b32_e32 v179, v149
	s_mov_b32 s20, 0x20000
	s_mov_b32 s21, 0
	v_lshl_add_u64 v[180:181], v[178:179], 0, s[20:21]
	global_load_dword v182, v[180:181], off
	global_load_dword v183, v[180:181], off offset:64
	global_load_dword v184, v[180:181], off offset:512
	global_load_dword v185, v[180:181], off offset:576
	v_mbcnt_hi_u32_b32 v148, -1, v169
	v_and_b32_e32 v145, 64, v148
	v_and_b32_e32 v147, 63, v144
	v_xor_b32_e32 v144, 16, v148
	v_add_u32_e32 v154, 64, v145
	v_cmp_lt_i32_e32 vcc, v144, v154
	s_lshl_b32 s2, s7, 2
	s_add_i32 s4, s2, 0
	v_cndmask_b32_e32 v144, v148, v144, vcc
	v_lshlrev_b32_e32 v149, 2, v144
	v_cmp_gt_u32_e64 s[0:1], 16, v147
	s_waitcnt vmcnt(4)
	v_pk_add_f32 v[126:127], v[126:127], v[134:135]
	v_pk_add_f32 v[124:125], v[124:125], v[132:133]
	v_pk_add_f32 v[122:123], v[122:123], v[138:139]
	v_pk_add_f32 v[120:121], v[120:121], v[136:137]
	v_pk_add_f32 v[118:119], v[118:119], v[142:143]
	v_pk_add_f32 v[116:117], v[116:117], v[140:141]
	v_pk_mul_f32 v[132:133], v[126:127], v[126:127]
	v_pk_mul_f32 v[134:135], v[124:125], v[124:125]
	v_pk_mul_f32 v[136:137], v[122:123], v[122:123]
	v_pk_mul_f32 v[138:139], v[120:121], v[120:121]
	v_pk_add_f32 v[114:115], v[114:115], v[152:153]
	v_pk_add_f32 v[112:113], v[112:113], v[150:151]
	v_pk_mul_f32 v[140:141], v[118:119], v[118:119]
	v_pk_mul_f32 v[142:143], v[116:117], v[116:117]
	v_add_f32_e32 v136, v136, v137
	v_add_f32_e32 v137, v138, v139
	v_add_f32_e32 v132, v132, v133
	v_add_f32_e32 v133, v134, v135
	v_pk_mul_f32 v[144:145], v[114:115], v[114:115]
	v_pk_mul_f32 v[150:151], v[112:113], v[112:113]
	v_add_f32_e32 v134, v140, v141
	v_add_f32_e32 v135, v142, v143
	v_add_f32_e32 v136, v137, v136
	v_add_f32_e32 v132, v133, v132
	v_add_f32_e32 v138, v144, v145
	v_add_f32_e32 v139, v150, v151
	v_add_f32_e32 v133, v135, v134
	v_add_f32_e32 v132, v132, v136
	v_add_f32_e32 v132, v132, v133
	v_add_f32_e32 v133, v139, v138
	v_add_f32_e32 v132, v132, v133
	ds_bpermute_b32 v133, v149, v132
	v_xor_b32_e32 v134, 32, v148
	v_cmp_lt_i32_e32 vcc, v134, v154
	v_lshl_add_u32 v150, v146, 4, s4
	s_waitcnt lgkmcnt(0)
	v_add_f32_e32 v132, v132, v133
	v_cndmask_b32_e32 v134, v148, v134, vcc
	v_lshlrev_b32_e32 v151, 2, v134
	ds_bpermute_b32 v133, v151, v132
	s_and_saveexec_b64 s[2:3], s[0:1]
	s_cbranch_execz .LBB0_668
	s_waitcnt lgkmcnt(0)
	v_add_f32_e32 v132, v132, v133
	ds_write_b32 v150, v132
.LBB0_668:
	s_or_b64 exec, exec, s[2:3]
	v_or_b32_e32 v132, 16, v130
	s_waitcnt lgkmcnt(0)
	v_ashrrev_i32_e32 v133, 31, v132
	v_lshlrev_b64 v[132:133], 13, v[132:133]
	v_lshl_add_u64 v[132:133], s[44:45], 0, v[132:133]
	v_lshl_add_u64 v[144:145], v[128:129], 2, v[132:133]
	global_load_dwordx4 v[132:135], v[144:145], off nt
	global_load_dwordx4 v[136:139], v[144:145], off offset:64 nt
	global_load_dwordx4 v[140:143], v[144:145], off offset:512 nt
	global_load_dwordx4 v[152:155], v[144:145], off offset:576 nt
	s_mov_b32 s20, 0x40000
	s_mov_b32 s21, 0
	v_lshl_add_u64 v[180:181], v[178:179], 0, s[20:21]
	global_load_dword v182, v[180:181], off
	global_load_dword v183, v[180:181], off offset:64
	global_load_dword v184, v[180:181], off offset:512
	global_load_dword v185, v[180:181], off offset:576
	s_waitcnt vmcnt(7)
	v_pk_add_f32 v[110:111], v[110:111], v[134:135]
	v_pk_add_f32 v[108:109], v[108:109], v[132:133]
	s_waitcnt vmcnt(6)
	v_pk_add_f32 v[106:107], v[106:107], v[138:139]
	v_pk_add_f32 v[104:105], v[104:105], v[136:137]
	s_waitcnt vmcnt(5)
	v_pk_add_f32 v[102:103], v[102:103], v[142:143]
	v_pk_add_f32 v[100:101], v[100:101], v[140:141]
	v_pk_mul_f32 v[132:133], v[110:111], v[110:111]
	v_pk_mul_f32 v[134:135], v[108:109], v[108:109]
	v_pk_mul_f32 v[136:137], v[106:107], v[106:107]
	v_pk_mul_f32 v[138:139], v[104:105], v[104:105]
	s_waitcnt vmcnt(4)
	v_pk_add_f32 v[98:99], v[98:99], v[154:155]
	v_pk_add_f32 v[96:97], v[96:97], v[152:153]
	v_pk_mul_f32 v[140:141], v[102:103], v[102:103]
	v_pk_mul_f32 v[142:143], v[100:101], v[100:101]
	v_add_f32_e32 v136, v136, v137
	v_add_f32_e32 v137, v138, v139
	v_add_f32_e32 v132, v132, v133
	v_add_f32_e32 v133, v134, v135
	v_pk_mul_f32 v[144:145], v[98:99], v[98:99]
	v_pk_mul_f32 v[152:153], v[96:97], v[96:97]
	v_add_f32_e32 v134, v140, v141
	v_add_f32_e32 v135, v142, v143
	v_add_f32_e32 v136, v137, v136
	v_add_f32_e32 v132, v133, v132
	v_add_f32_e32 v138, v144, v145
	v_add_f32_e32 v139, v152, v153
	v_add_f32_e32 v133, v135, v134
	v_add_f32_e32 v132, v132, v136
	v_add_f32_e32 v132, v132, v133
	v_add_f32_e32 v133, v139, v138
	v_add_f32_e32 v132, v132, v133
	ds_bpermute_b32 v133, v149, v132
	s_waitcnt lgkmcnt(0)
	v_add_f32_e32 v132, v132, v133
	ds_bpermute_b32 v133, v151, v132
	s_and_saveexec_b64 s[2:3], s[0:1]
	s_cbranch_execz .LBB0_670
	s_waitcnt lgkmcnt(0)
	v_add_f32_e32 v132, v132, v133
	ds_write_b32 v150, v132 offset:256
.LBB0_670:
	s_or_b64 exec, exec, s[2:3]
	v_or_b32_e32 v132, 32, v130
	s_waitcnt lgkmcnt(0)
	v_ashrrev_i32_e32 v133, 31, v132
	v_lshlrev_b64 v[132:133], 13, v[132:133]
	v_lshl_add_u64 v[132:133], s[44:45], 0, v[132:133]
	v_lshl_add_u64 v[144:145], v[128:129], 2, v[132:133]
	global_load_dwordx4 v[132:135], v[144:145], off nt
	global_load_dwordx4 v[136:139], v[144:145], off offset:64 nt
	global_load_dwordx4 v[140:143], v[144:145], off offset:512 nt
	global_load_dwordx4 v[152:155], v[144:145], off offset:576 nt
	s_mov_b32 s20, 0x60000
	s_mov_b32 s21, 0
	v_lshl_add_u64 v[180:181], v[178:179], 0, s[20:21]
	global_load_dword v182, v[180:181], off
	global_load_dword v183, v[180:181], off offset:64
	global_load_dword v184, v[180:181], off offset:512
	global_load_dword v185, v[180:181], off offset:576
	s_waitcnt vmcnt(7)
	v_pk_add_f32 v[94:95], v[94:95], v[134:135]
	v_pk_add_f32 v[92:93], v[92:93], v[132:133]
	s_waitcnt vmcnt(6)
	v_pk_add_f32 v[90:91], v[90:91], v[138:139]
	v_pk_add_f32 v[88:89], v[88:89], v[136:137]
	s_waitcnt vmcnt(5)
	v_pk_add_f32 v[86:87], v[86:87], v[142:143]
	v_pk_add_f32 v[84:85], v[84:85], v[140:141]
	v_pk_mul_f32 v[132:133], v[94:95], v[94:95]
	v_pk_mul_f32 v[134:135], v[92:93], v[92:93]
	v_pk_mul_f32 v[136:137], v[90:91], v[90:91]
	v_pk_mul_f32 v[138:139], v[88:89], v[88:89]
	s_waitcnt vmcnt(4)
	v_pk_add_f32 v[82:83], v[82:83], v[154:155]
	v_pk_add_f32 v[80:81], v[80:81], v[152:153]
	v_pk_mul_f32 v[140:141], v[86:87], v[86:87]
	v_pk_mul_f32 v[142:143], v[84:85], v[84:85]
	v_add_f32_e32 v136, v136, v137
	v_add_f32_e32 v137, v138, v139
	v_add_f32_e32 v132, v132, v133
	v_add_f32_e32 v133, v134, v135
	v_pk_mul_f32 v[144:145], v[82:83], v[82:83]
	v_pk_mul_f32 v[152:153], v[80:81], v[80:81]
	v_add_f32_e32 v134, v140, v141
	v_add_f32_e32 v135, v142, v143
	v_add_f32_e32 v136, v137, v136
	v_add_f32_e32 v132, v133, v132
	v_add_f32_e32 v138, v144, v145
	v_add_f32_e32 v139, v152, v153
	v_add_f32_e32 v133, v135, v134
	v_add_f32_e32 v132, v132, v136
	v_add_f32_e32 v132, v132, v133
	v_add_f32_e32 v133, v139, v138
	v_add_f32_e32 v132, v132, v133
	ds_bpermute_b32 v133, v149, v132
	s_waitcnt lgkmcnt(0)
	v_add_f32_e32 v132, v132, v133
	ds_bpermute_b32 v133, v151, v132
	s_and_saveexec_b64 s[2:3], s[0:1]
	s_cbranch_execz .LBB0_672
	s_waitcnt lgkmcnt(0)
	v_add_f32_e32 v132, v132, v133
	ds_write_b32 v150, v132 offset:512
.LBB0_672:
	s_or_b64 exec, exec, s[2:3]
	v_or_b32_e32 v132, 48, v130
	s_waitcnt lgkmcnt(0)
	v_ashrrev_i32_e32 v133, 31, v132
	v_lshlrev_b64 v[132:133], 13, v[132:133]
	v_lshl_add_u64 v[132:133], s[44:45], 0, v[132:133]
	v_lshl_add_u64 v[144:145], v[128:129], 2, v[132:133]
	global_load_dwordx4 v[132:135], v[144:145], off nt
	global_load_dwordx4 v[136:139], v[144:145], off offset:64 nt
	global_load_dwordx4 v[140:143], v[144:145], off offset:512 nt
	global_load_dwordx4 v[152:155], v[144:145], off offset:576 nt
	s_mov_b32 s20, 0x100000
	s_mov_b32 s21, 0
	v_lshl_add_u64 v[180:181], v[178:179], 0, s[20:21]
	global_load_dword v182, v[180:181], off
	global_load_dword v183, v[180:181], off offset:64
	global_load_dword v184, v[180:181], off offset:512
	global_load_dword v185, v[180:181], off offset:576
	s_waitcnt vmcnt(7)
	v_pk_add_f32 v[78:79], v[78:79], v[134:135]
	v_pk_add_f32 v[76:77], v[76:77], v[132:133]
	s_waitcnt vmcnt(6)
	v_pk_add_f32 v[74:75], v[74:75], v[138:139]
	v_pk_add_f32 v[72:73], v[72:73], v[136:137]
	s_waitcnt vmcnt(5)
	v_pk_add_f32 v[70:71], v[70:71], v[142:143]
	v_pk_add_f32 v[68:69], v[68:69], v[140:141]
	v_pk_mul_f32 v[132:133], v[78:79], v[78:79]
	v_pk_mul_f32 v[134:135], v[76:77], v[76:77]
	v_pk_mul_f32 v[136:137], v[74:75], v[74:75]
	v_pk_mul_f32 v[138:139], v[72:73], v[72:73]
	s_waitcnt vmcnt(4)
	v_pk_add_f32 v[66:67], v[66:67], v[154:155]
	v_pk_add_f32 v[64:65], v[64:65], v[152:153]
	v_pk_mul_f32 v[140:141], v[70:71], v[70:71]
	v_pk_mul_f32 v[142:143], v[68:69], v[68:69]
	v_add_f32_e32 v136, v136, v137
	v_add_f32_e32 v137, v138, v139
	v_add_f32_e32 v132, v132, v133
	v_add_f32_e32 v133, v134, v135
	v_pk_mul_f32 v[144:145], v[66:67], v[66:67]
	v_pk_mul_f32 v[152:153], v[64:65], v[64:65]
	v_add_f32_e32 v134, v140, v141
	v_add_f32_e32 v135, v142, v143
	v_add_f32_e32 v136, v137, v136
	v_add_f32_e32 v132, v133, v132
	v_add_f32_e32 v138, v144, v145
	v_add_f32_e32 v139, v152, v153
	v_add_f32_e32 v133, v135, v134
	v_add_f32_e32 v132, v132, v136
	v_add_f32_e32 v132, v132, v133
	v_add_f32_e32 v133, v139, v138
	v_add_f32_e32 v132, v132, v133
	ds_bpermute_b32 v133, v149, v132
	s_waitcnt lgkmcnt(0)
	v_add_f32_e32 v132, v132, v133
	ds_bpermute_b32 v133, v151, v132
	s_and_saveexec_b64 s[2:3], s[0:1]
	s_cbranch_execz .LBB0_674
	s_waitcnt lgkmcnt(0)
	v_add_f32_e32 v132, v132, v133
	ds_write_b32 v150, v132 offset:768
.LBB0_674:
	s_or_b64 exec, exec, s[2:3]
	s_waitcnt lgkmcnt(0)
	v_lshlrev_b64 v[132:133], 13, v[130:131]
	v_lshl_add_u64 v[132:133], s[44:45], 0, v[132:133]
	v_lshl_add_u64 v[132:133], v[128:129], 2, v[132:133]
	s_mov_b64 s[2:3], 0x100000
	v_lshl_add_u64 v[152:153], v[132:133], 0, s[2:3]
	v_add_co_u32_e32 v142, vcc, 0x100000, v132
	global_load_dwordx4 v[134:137], v[152:153], off offset:64 nt
	global_load_dwordx4 v[138:141], v[152:153], off offset:512 nt
	v_addc_co_u32_e32 v143, vcc, 0, v133, vcc
	global_load_dwordx4 v[142:145], v[142:143], off nt
	s_nop 0
	global_load_dwordx4 v[152:155], v[152:153], off offset:576 nt
	s_mov_b32 s20, 0x120000
	s_mov_b32 s21, 0
	v_lshl_add_u64 v[180:181], v[178:179], 0, s[20:21]
	global_load_dword v182, v[180:181], off
	global_load_dword v183, v[180:181], off offset:64
	global_load_dword v184, v[180:181], off offset:512
	global_load_dword v185, v[180:181], off offset:576
	v_add_u32_e32 v148, 0x80, v146
	s_waitcnt vmcnt(7)
	v_pk_add_f32 v[58:59], v[58:59], v[136:137]
	v_pk_add_f32 v[56:57], v[56:57], v[134:135]
	s_waitcnt vmcnt(6)
	v_pk_add_f32 v[54:55], v[54:55], v[140:141]
	s_waitcnt vmcnt(5)
	v_pk_add_f32 v[62:63], v[62:63], v[144:145]
	v_pk_add_f32 v[60:61], v[60:61], v[142:143]
	v_pk_add_f32 v[52:53], v[52:53], v[138:139]
	v_pk_mul_f32 v[134:135], v[58:59], v[58:59]
	v_pk_mul_f32 v[136:137], v[56:57], v[56:57]
	v_pk_mul_f32 v[138:139], v[54:55], v[54:55]
	v_pk_mul_f32 v[142:143], v[62:63], v[62:63]
	v_pk_mul_f32 v[144:145], v[60:61], v[60:61]
	v_pk_mul_f32 v[140:141], v[52:53], v[52:53]
	s_waitcnt vmcnt(4)
	v_pk_add_f32 v[50:51], v[50:51], v[154:155]
	v_pk_add_f32 v[48:49], v[48:49], v[152:153]
	v_add_f32_e32 v134, v134, v135
	v_add_f32_e32 v135, v136, v137
	v_add_f32_e32 v136, v138, v139
	v_add_f32_e32 v138, v142, v143
	v_add_f32_e32 v139, v144, v145
	v_pk_mul_f32 v[152:153], v[50:51], v[50:51]
	v_pk_mul_f32 v[154:155], v[48:49], v[48:49]
	v_add_f32_e32 v137, v140, v141
	v_add_f32_e32 v134, v135, v134
	v_add_f32_e32 v138, v139, v138
	v_add_f32_e32 v135, v137, v136
	v_add_f32_e32 v136, v152, v153
	v_add_f32_e32 v137, v154, v155
	v_add_f32_e32 v134, v138, v134
	v_add_f32_e32 v134, v134, v135
	v_add_f32_e32 v135, v137, v136
	v_add_f32_e32 v134, v134, v135
	ds_bpermute_b32 v135, v149, v134
	s_waitcnt lgkmcnt(0)
	v_add_f32_e32 v134, v134, v135
	ds_bpermute_b32 v135, v151, v134
	s_and_saveexec_b64 s[2:3], s[0:1]
	s_cbranch_execz .LBB0_676
	v_lshl_add_u32 v136, v148, 4, s4
	s_waitcnt lgkmcnt(0)
	v_add_f32_e32 v134, v134, v135
	ds_write_b32 v136, v134
.LBB0_676:
	s_or_b64 exec, exec, s[2:3]
	v_add_co_u32_e32 v134, vcc, 0x120000, v132
	s_mov_b64 s[2:3], 0x120000
	s_waitcnt lgkmcnt(0)
	v_addc_co_u32_e32 v135, vcc, 0, v133, vcc
	global_load_dwordx4 v[134:137], v[134:135], off nt
	v_lshl_add_u64 v[132:133], v[132:133], 0, s[2:3]
	global_load_dwordx4 v[138:141], v[132:133], off offset:64 nt
	global_load_dwordx4 v[142:145], v[132:133], off offset:512 nt
	global_load_dwordx4 v[152:155], v[132:133], off offset:576 nt
	s_mov_b32 s20, 0x140000
	s_mov_b32 s21, 0
	v_lshl_add_u64 v[180:181], v[178:179], 0, s[20:21]
	global_load_dword v182, v[180:181], off
	global_load_dword v183, v[180:181], off offset:64
	global_load_dword v184, v[180:181], off offset:512
	global_load_dword v185, v[180:181], off offset:576
	s_waitcnt vmcnt(6)
	v_pk_add_f32 v[42:43], v[42:43], v[140:141]
	v_pk_add_f32 v[46:47], v[46:47], v[136:137]
	v_pk_add_f32 v[44:45], v[44:45], v[134:135]
	v_pk_add_f32 v[40:41], v[40:41], v[138:139]
	s_waitcnt vmcnt(5)
	v_pk_add_f32 v[38:39], v[38:39], v[144:145]
	v_pk_add_f32 v[36:37], v[36:37], v[142:143]
	v_pk_mul_f32 v[132:133], v[46:47], v[46:47]
	v_pk_mul_f32 v[134:135], v[44:45], v[44:45]
	v_pk_mul_f32 v[136:137], v[42:43], v[42:43]
	v_pk_mul_f32 v[138:139], v[40:41], v[40:41]
	s_waitcnt vmcnt(4)
	v_pk_add_f32 v[34:35], v[34:35], v[154:155]
	v_pk_add_f32 v[32:33], v[32:33], v[152:153]
	v_pk_mul_f32 v[140:141], v[38:39], v[38:39]
	v_pk_mul_f32 v[142:143], v[36:37], v[36:37]
	v_add_f32_e32 v132, v132, v133
	v_add_f32_e32 v133, v134, v135
	v_add_f32_e32 v134, v136, v137
	v_add_f32_e32 v135, v138, v139
	v_pk_mul_f32 v[144:145], v[34:35], v[34:35]
	v_pk_mul_f32 v[152:153], v[32:33], v[32:33]
	v_add_f32_e32 v136, v140, v141
	v_add_f32_e32 v137, v142, v143
	v_add_f32_e32 v132, v133, v132
	v_add_f32_e32 v133, v135, v134
	v_add_f32_e32 v138, v144, v145
	v_add_f32_e32 v139, v152, v153
	v_add_f32_e32 v134, v137, v136
	v_add_f32_e32 v132, v132, v133
	v_add_f32_e32 v132, v132, v134
	v_add_f32_e32 v133, v139, v138
	v_add_f32_e32 v132, v132, v133
	ds_bpermute_b32 v133, v149, v132
	s_waitcnt lgkmcnt(0)
	v_add_f32_e32 v132, v132, v133
	ds_bpermute_b32 v133, v151, v132
	s_and_saveexec_b64 s[2:3], s[0:1]
	s_cbranch_execz .LBB0_678
	s_waitcnt lgkmcnt(0)
	v_add_f32_e32 v132, v132, v133
	ds_write_b32 v150, v132 offset:2304
.LBB0_678:
	s_or_b64 exec, exec, s[2:3]
	v_lshlrev_b64 v[130:131], 13, v[130:131]
	v_lshl_add_u64 v[130:131], s[44:45], 0, v[130:131]
	v_lshl_add_u64 v[130:131], v[128:129], 2, v[130:131]
	s_mov_b64 s[2:3], 0x140000
	v_lshl_add_u64 v[144:145], v[130:131], 0, s[2:3]
	v_add_co_u32_e32 v140, vcc, 0x140000, v130
	s_waitcnt lgkmcnt(0)
	global_load_dwordx4 v[132:135], v[144:145], off offset:64 nt
	global_load_dwordx4 v[136:139], v[144:145], off offset:512 nt
	v_addc_co_u32_e32 v141, vcc, 0, v131, vcc
	global_load_dwordx4 v[140:143], v[140:141], off nt
	s_nop 0
	global_load_dwordx4 v[152:155], v[144:145], off offset:576 nt
	s_mov_b32 s20, 0x160000
	s_mov_b32 s21, 0
	v_lshl_add_u64 v[180:181], v[178:179], 0, s[20:21]
	global_load_dword v182, v[180:181], off
	global_load_dword v183, v[180:181], off offset:64
	global_load_dword v184, v[180:181], off offset:512
	global_load_dword v185, v[180:181], off offset:576
	s_waitcnt vmcnt(7)
	v_pk_add_f32 v[26:27], v[26:27], v[134:135]
	v_pk_add_f32 v[24:25], v[24:25], v[132:133]
	s_waitcnt vmcnt(6)
	v_pk_add_f32 v[22:23], v[22:23], v[138:139]
	s_waitcnt vmcnt(5)
	v_pk_add_f32 v[30:31], v[30:31], v[142:143]
	v_pk_add_f32 v[28:29], v[28:29], v[140:141]
	v_pk_add_f32 v[20:21], v[20:21], v[136:137]
	v_pk_mul_f32 v[132:133], v[26:27], v[26:27]
	v_pk_mul_f32 v[134:135], v[24:25], v[24:25]
	v_pk_mul_f32 v[136:137], v[22:23], v[22:23]
	v_pk_mul_f32 v[140:141], v[30:31], v[30:31]
	v_pk_mul_f32 v[142:143], v[28:29], v[28:29]
	v_pk_mul_f32 v[138:139], v[20:21], v[20:21]
	s_waitcnt vmcnt(4)
	v_pk_add_f32 v[18:19], v[18:19], v[154:155]
	v_pk_add_f32 v[16:17], v[16:17], v[152:153]
	v_add_f32_e32 v132, v132, v133
	v_add_f32_e32 v133, v134, v135
	v_add_f32_e32 v134, v136, v137
	v_add_f32_e32 v136, v140, v141
	v_add_f32_e32 v137, v142, v143
	v_pk_mul_f32 v[144:145], v[18:19], v[18:19]
	v_pk_mul_f32 v[152:153], v[16:17], v[16:17]
	v_add_f32_e32 v135, v138, v139
	v_add_f32_e32 v132, v133, v132
	v_add_f32_e32 v136, v137, v136
	v_add_f32_e32 v133, v135, v134
	v_add_f32_e32 v134, v144, v145
	v_add_f32_e32 v135, v152, v153
	v_add_f32_e32 v132, v136, v132
	v_add_f32_e32 v132, v132, v133
	v_add_f32_e32 v133, v135, v134
	v_add_f32_e32 v132, v132, v133
	ds_bpermute_b32 v133, v149, v132
	s_waitcnt lgkmcnt(0)
	v_add_f32_e32 v132, v132, v133
	ds_bpermute_b32 v133, v151, v132
	s_and_saveexec_b64 s[2:3], s[0:1]
	s_cbranch_execz .LBB0_680
	s_waitcnt lgkmcnt(0)
	v_add_f32_e32 v132, v132, v133
	ds_write_b32 v150, v132 offset:2560
